# v16: v15 + attention-B loop: drop redundant NEG re-inits (64/iter) and 24 spill readlanes of a splat constant
# speedup vs baseline: 1.0022x; 1.0022x over previous
; #define SBAR() __builtin_amdgcn_sched_barrier(0)
; __device__ __forceinline__ void finishSM(f32x16& p0, f32x16& p1, float& l_reg, bf16x8& pa0, bf16x8& pa1, bf16x8& pa2, bf16x8& pa3) {
;     ...
;     PK4(p0, 0, pa0); PK4(p0, 8, pa1); PK4(p1, 0, pa2); PK4(p1, 8, pa3);
;     ...
; }
; __device__ __forceinline__ void qkt(f32x16& p0, f32x16& p1, const char* Ks, const bf16x8* qr, float c0, int r32, int hi, int half) {
;     ...
;     bf16x8 a0 = KFRAG(0, r32), a1 = KFRAG(0, 32 + r32), b0 = KFRAG(1, r32), b1 = KFRAG(1, 32 + r32);
;     SBAR();
; #pragma unroll
;     for (int r = 0; r < 16; ++r) { p0[r] = c0; p1[r] = c0; }
;     SBAR();
;     p0 = __builtin_amdgcn_mfma_f32_32x32x16_bf16(a0, qr[0], p0, 0, 0, 0); p1 = __builtin_amdgcn_mfma_f32_32x32x16_bf16(a1, qr[0], p1, 0, 0, 0);
;     a0 = KFRAG(2, r32); a1 = KFRAG(2, 32 + r32);
;     SBAR();
;     p0 = __builtin_amdgcn_mfma_f32_32x32x16_bf16(b0, qr[1], p0, 0, 0, 0); p1 = __builtin_amdgcn_mfma_f32_32x32x16_bf16(b1, qr[1], p1, 0, 0, 0);
;     b0 = KFRAG(3, r32); b1 = KFRAG(3, 32 + r32);
;     SBAR();
;     p0 = __builtin_amdgcn_mfma_f32_32x32x16_bf16(a0, qr[2], p0, 0, 0, 0); p1 = __builtin_amdgcn_mfma_f32_32x32x16_bf16(a1, qr[2], p1, 0, 0, 0);
;     p0 = __builtin_amdgcn_mfma_f32_32x32x16_bf16(b0, qr[3], p0, 0, 0, 0); p1 = __builtin_amdgcn_mfma_f32_32x32x16_bf16(b1, qr[3], p1, 0, 0, 0);
; template <int MODE>
; __device__ __forceinline__ void attn_unit(const UnitArgs& A, char* lds, const int wave_) {
;     ...
;     auto zone_of = [&](int t) -> int { const int k0 = 64 * t, qw0 = A.q0 + 32 * qb; return (k0 + 63 - qw0 <= -128) ? 0 : ((k0 - qw0 - 31 >= 128) ? 2 : 1); };
;     ...
;     auto post = [&](f32x16& p0, f32x16& p1, int t) {
;         SBAR();
;         if (MODE == 0) {
;             if (zone_of(t) == 1) { const int k0 = 64 * t, qw0 = A.q0 + 32 * qb;
;                 const float* b = lutA + A.h * LUTA_STRIDE + (k0 - qw0 - r32 + 4 * hi + 320);
; #pragma unroll
;                 for (int r = 0; r < 16; ++r) { const int c = (r & 3) + 8 * (r >> 2); p0[r] += b[c]; p1[r] += b[32 + c]; } }
;         } else if (MODE == 1) {
;             const int kr = A.tile0 + t, rq = A.q0 + (qb >> 1);
;             int rs = rq - 4; rs = rs < 0 ? 0 : rs; rs = rs > A.R - 8 ? A.R - 8 : rs;
;             if (kr < rs || kr >= rs + 8) {
; #pragma unroll
;                 for (int r = 0; r < 16; ++r) { p0[r] = NEG; p1[r] = NEG; }
.LBB0_422:
	ds_read_b128 v[32:35], v113 offset:49152
	ds_read_b128 v[96:99], v113 offset:57344
	ds_read_b128 v[100:103], v114 offset:49152
	ds_read_b128 v[186:189], v114 offset:57344
	v_readlane_b32 s72, v255, 10
	v_readlane_b32 s73, v255, 11
	s_nop 1
	v_mov_b64_e32 v[64:65], s[72:73]
	v_mov_b64_e32 v[66:67], s[72:73]
	v_mov_b64_e32 v[68:69], s[72:73]
	v_mov_b64_e32 v[70:71], s[72:73]
	v_mov_b64_e32 v[72:73], s[72:73]
	v_mov_b64_e32 v[74:75], s[72:73]
	v_mov_b64_e32 v[76:77], s[72:73]
	v_mov_b64_e32 v[78:79], s[72:73]
	s_waitcnt lgkmcnt(3)
	s_nop 0
	v_mfma_f32_32x32x16_bf16 v[48:63], v[32:35], v[92:95], v[64:79]
	s_waitcnt lgkmcnt(2)
	v_mfma_f32_32x32x16_bf16 v[32:47], v[96:99], v[92:95], v[64:79]
	s_nop 6
	ds_read_b128 v[64:67], v115 offset:49152
	ds_read_b128 v[68:71], v115 offset:57344
	s_waitcnt lgkmcnt(3)
	v_mfma_f32_32x32x16_bf16 v[48:63], v[100:103], v[88:91], v[48:63]
	ds_read_b128 v[72:75], v116 offset:49152
	ds_read_b128 v[76:79], v116 offset:57344
	s_waitcnt lgkmcnt(4)
	v_mfma_f32_32x32x16_bf16 v[32:47], v[186:189], v[88:91], v[32:47]
	s_waitcnt lgkmcnt(3)
	v_mfma_f32_32x32x16_bf16 v[48:63], v[64:67], v[84:87], v[48:63]
	v_cvt_pk_bf16_f32 v64, v117, v118
	v_cvt_pk_bf16_f32 v65, v119, v120
	v_cvt_pk_bf16_f32 v66, v121, v122
	v_cvt_pk_bf16_f32 v67, v123, v124
	v_cvt_pk_bf16_f32 v96, v134, v135
	v_cvt_pk_bf16_f32 v97, v136, v137
	v_cvt_pk_bf16_f32 v98, v138, v139
	s_waitcnt lgkmcnt(2)
	v_mfma_f32_32x32x16_bf16 v[32:47], v[68:71], v[84:87], v[32:47]
	v_cvt_pk_bf16_f32 v99, v140, v141
	v_cvt_pk_bf16_f32 v100, v142, v143
	v_cvt_pk_bf16_f32 v101, v152, v153
	v_cvt_pk_bf16_f32 v102, v154, v155
	v_cvt_pk_bf16_f32 v103, v156, v157
	v_permlane32_swap_b32_e32 v64, v66
	s_waitcnt lgkmcnt(1)
	v_mfma_f32_32x32x16_bf16 v[48:63], v[72:75], v[80:83], v[48:63]
	v_permlane32_swap_b32_e32 v65, v67
	v_permlane32_swap_b32_e32 v96, v98
	v_permlane32_swap_b32_e32 v97, v99
	v_permlane32_swap_b32_e32 v100, v102
	s_waitcnt lgkmcnt(0)
	v_mfma_f32_32x32x16_bf16 v[32:47], v[76:79], v[80:83], v[32:47]
	v_cvt_pk_bf16_f32 v76, v125, v126
	v_cvt_pk_bf16_f32 v77, v127, v128
	v_cvt_pk_bf16_f32 v78, v129, v130
	v_cvt_pk_bf16_f32 v79, v131, v132
	s_nop 0
	v_permlane32_swap_b32_e32 v76, v78
	v_permlane32_swap_b32_e32 v77, v79
	v_permlane32_swap_b32_e32 v101, v103
	s_add_i32 s1, s88, s97
	s_add_i32 s0, s1, 2
	s_min_i32 s72, s0, s71
	s_lshl_b32 s73, s72, 6
	s_mul_i32 s74, s72, 0x50000
	s_mul_hi_i32 s75, s73, 0x1400
	s_add_u32 s72, s33, s74
	s_addc_u32 s73, s92, s75
	s_add_u32 s74, s89, s74
	s_addc_u32 s75, s2, s75
	v_lshl_add_u64 v[68:69], s[74:75], 0, v[144:145]
	v_add_co_u32_e32 v72, vcc, vcc_lo, v68
	s_and_b32 s74, s96, 0x4000
	s_nop 0
	v_addc_co_u32_e32 v73, vcc, 0, v69, vcc
	global_load_dwordx4 v[68:71], v[68:69], off
	s_nop 0
	global_load_dwordx4 v[72:75], v[72:73], off
	v_lshl_add_u64 v[180:181], s[72:73], 0, v[104:105]
	s_mov_b64 s[72:73], 0xe00
	s_add_i32 s74, s74, s70
	v_lshl_add_u64 v[182:183], v[180:181], 0, s[72:73]
	s_mov_b32 s72, m0
	s_mov_b32 m0, s74
	s_nop 0
	global_load_lds_dwordx4 v[182:183], off
	s_mov_b32 m0, s72
	s_mov_b64 s[72:73], 0x28e00
	v_lshl_add_u64 v[180:181], v[180:181], 0, s[72:73]
	s_addk_i32 s74, 0x2000
	s_mov_b32 s72, m0
	s_mov_b32 m0, s74
	s_nop 0
	global_load_lds_dwordx4 v[180:181], off
	s_mov_b32 m0, s72
	s_add_i32 s74, s1, 1
	s_cmp_ge_u32 s74, s3
	s_cselect_b64 s[72:73], -1, 0
	s_cmp_lt_u32 s74, s91
	s_cselect_b64 s[74:75], -1, 0
	s_and_b64 s[72:73], s[72:73], s[74:75]
	v_mov_b32_e32 v197, 0xf149f2ca
	s_andn2_b64 vcc, exec, s[72:73]
	v_mov_b32_e32 v196, 0xf149f2ca
	v_mov_b32_e32 v195, 0xf149f2ca
	v_mov_b32_e32 v194, 0xf149f2ca
	v_mov_b32_e32 v193, 0xf149f2ca
	v_mov_b32_e32 v192, 0xf149f2ca
	v_mov_b32_e32 v191, 0xf149f2ca
	v_mov_b32_e32 v190, 0xf149f2ca
	v_mov_b32_e32 v189, 0xf149f2ca
	v_mov_b32_e32 v188, 0xf149f2ca
	v_mov_b32_e32 v187, 0xf149f2ca
	v_mov_b32_e32 v186, 0xf149f2ca
	v_mov_b32_e32 v185, 0xf149f2ca
	v_mov_b32_e32 v181, 0xf149f2ca
	v_mov_b32_e32 v180, 0xf149f2ca
	v_mov_b32_e32 v179, 0xf149f2ca
	v_mov_b32_e32 v212, 0xf149f2ca
	v_mov_b32_e32 v211, 0xf149f2ca
	v_mov_b32_e32 v210, 0xf149f2ca
	v_mov_b32_e32 v209, 0xf149f2ca
	v_mov_b32_e32 v208, 0xf149f2ca
	v_mov_b32_e32 v207, 0xf149f2ca
	v_mov_b32_e32 v206, 0xf149f2ca
	v_mov_b32_e32 v205, 0xf149f2ca
	v_mov_b32_e32 v204, 0xf149f2ca
	v_mov_b32_e32 v203, 0xf149f2ca
	v_mov_b32_e32 v202, 0xf149f2ca
	v_mov_b32_e32 v201, 0xf149f2ca
	v_mov_b32_e32 v200, 0xf149f2ca
	v_mov_b32_e32 v199, 0xf149f2ca
	v_mov_b32_e32 v198, 0xf149f2ca
	v_mov_b32_e32 v213, 0xf149f2ca
	s_cbranch_vccnz .LBB0_488
; #define SBAR() __builtin_amdgcn_sched_barrier(0)
; #define PVLOAD(D0, X) do { X[0] = tr_read<v_rd_off(D0, 0, 0)>(vb); X[1] = tr_read<v_rd_off(D0, 0, 1)>(vb); X[2] = tr_read<v_rd_off(D0, 1, 0)>(vb); X[3] = tr_read<v_rd_off(D0, 1, 1)>(vb); \
;     X[4] = tr_read<v_rd_off(D0, 2, 0)>(vb); X[5] = tr_read<v_rd_off(D0, 2, 1)>(vb); X[6] = tr_read<v_rd_off(D0, 3, 0)>(vb); X[7] = tr_read<v_rd_off(D0, 3, 1)>(vb); } while (0)
; #define PVMMA(OD, X) do { OD = __builtin_amdgcn_mfma_f32_32x32x16_bf16(pa0, PVPK(X[0], X[1]), OD, 0, 0, 0); OD = __builtin_amdgcn_mfma_f32_32x32x16_bf16(pa1, PVPK(X[2], X[3]), OD, 0, 0, 0); \
;     OD = __builtin_amdgcn_mfma_f32_32x32x16_bf16(pa2, PVPK(X[4], X[5]), OD, 0, 0, 0); OD = __builtin_amdgcn_mfma_f32_32x32x16_bf16(pa3, PVPK(X[6], X[7]), OD, 0, 0, 0); } while (0)
; #define PVWAIT() do { asm volatile("s_waitcnt lgkmcnt(0)" ::: "memory"); SBAR(); } while (0)
; #define PVEXP(P, B, N) do { _Pragma("unroll") for (int r = (B); r < (B) + (N); ++r) P[r] = __builtin_amdgcn_exp2f(P[r]); } while (0)
; template <int NB> __device__ __forceinline__ void pv_blocks(f32x16* o, int vb, bf16x8 pa0, bf16x8 pa1, bf16x8 pa2, bf16x8 pa3, f32x16& pe0, f32x16& pe1) {
;     s16x4 x[8], y[8];
;     ...
;     PVLOAD(0, x); PVWAIT();
;     if (NB == 4) {
;         PVLOAD(1, y); SBAR(); PVMMA(o[0], x); PVEXP(pe0, 0, 8); SBAR(); PVWAIT();
;         PVLOAD(2, x); SBAR(); PVMMA(o[1], y); PVEXP(pe0, 8, 8); SBAR(); PVWAIT();
;         PVLOAD(3, y); SBAR(); PVMMA(o[2], x); PVEXP(pe1, 0, 8); SBAR(); PVWAIT();
;         PVMMA(o[3], y); PVEXP(pe1, 8, 8);
;     } else {
;         PVLOAD(1, y); SBAR(); PVMMA(o[0], x); PVEXP(pe0, 0, 16); SBAR(); PVWAIT();
;         PVMMA(o[1], y); PVEXP(pe1, 0, 16);
;     }
; template <int MODE>
; __device__ __forceinline__ void attn_unit(const UnitArgs& A, char* lds, const int wave_) {
;     ...
;             } else {
;                 const int c = 32 * (qb & 1) + r32; int cs = c - 8; cs = cs < 0 ? 0 : cs; cs = cs > 48 ? 48 : cs;
;                 const float* b = lutB + ((2 * A.h + half) * 15 + (kr - rq + 7)) * 128 + 64 + 4 * hi - c;
; #pragma unroll
;                 for (int r = 0; r < 16; ++r) { const int cc = (r & 3) + 8 * (r >> 2), j = 4 * hi + cc;
;                     p0[r] = ((unsigned)(j - cs) < 16u) ? p0[r] + b[cc] : NEG; p1[r] = ((unsigned)(j + 32 - cs) < 16u) ? p1[r] + b[32 + cc] : NEG; } }
	ds_read2_b32 v[246:247], v178 offset0:0 offset1:32
	ds_read2_b32 v[248:249], v178 offset0:1 offset1:33
	ds_read2_b32 v[250:251], v178 offset0:2 offset1:34
	ds_read2_b32 v[252:253], v178 offset0:3 offset1:35
	s_waitcnt lgkmcnt(0)
	s_mov_b64 exec, s[68:69]
	v_add_f32_e32 v179, v48, v246
	s_mov_b64 exec, s[4:5]
	v_add_f32_e32 v198, v32, v247
	s_mov_b64 exec, s[6:7]
	v_add_f32_e32 v180, v49, v248
	s_mov_b64 exec, s[8:9]
	v_add_f32_e32 v199, v33, v249
	s_mov_b64 exec, s[10:11]
	v_add_f32_e32 v181, v50, v250
	s_mov_b64 exec, s[12:13]
	v_add_f32_e32 v200, v34, v251
	s_mov_b64 exec, s[14:15]
	v_add_f32_e32 v185, v51, v252
	s_mov_b64 exec, s[16:17]
	v_add_f32_e32 v201, v35, v253
	s_mov_b64 exec, -1
	ds_read2_b32 v[246:247], v178 offset0:8 offset1:40
	ds_read2_b32 v[248:249], v178 offset0:9 offset1:41
	ds_read2_b32 v[250:251], v178 offset0:10 offset1:42
	ds_read2_b32 v[252:253], v178 offset0:11 offset1:43
	s_waitcnt lgkmcnt(0)
	s_mov_b64 exec, s[18:19]
	v_add_f32_e32 v186, v52, v246
	s_mov_b64 exec, s[20:21]
	v_add_f32_e32 v202, v36, v247
	s_mov_b64 exec, s[22:23]
	v_add_f32_e32 v187, v53, v248
	s_mov_b64 exec, s[24:25]
	v_add_f32_e32 v203, v37, v249
	s_mov_b64 exec, s[26:27]
	v_add_f32_e32 v188, v54, v250
	s_mov_b64 exec, s[28:29]
	v_add_f32_e32 v204, v38, v251
	s_mov_b64 exec, s[30:31]
	v_add_f32_e32 v189, v55, v252
	s_mov_b64 exec, s[34:35]
	v_add_f32_e32 v205, v39, v253
	s_mov_b64 exec, -1
	ds_read2_b32 v[246:247], v178 offset0:16 offset1:48
	ds_read2_b32 v[248:249], v178 offset0:17 offset1:49
	ds_read2_b32 v[250:251], v178 offset0:18 offset1:50
	ds_read2_b32 v[252:253], v178 offset0:19 offset1:51
	s_waitcnt lgkmcnt(0)
	s_mov_b64 exec, s[36:37]
	v_add_f32_e32 v190, v56, v246
	s_mov_b64 exec, s[38:39]
	v_add_f32_e32 v206, v40, v247
	s_mov_b64 exec, s[40:41]
	v_add_f32_e32 v191, v57, v248
	s_mov_b64 exec, s[42:43]
	v_add_f32_e32 v207, v41, v249
	s_mov_b64 exec, s[44:45]
	v_add_f32_e32 v192, v58, v250
	s_mov_b64 exec, s[46:47]
	v_add_f32_e32 v208, v42, v251
	s_mov_b64 exec, s[48:49]
	v_add_f32_e32 v193, v59, v252
	s_mov_b64 exec, s[50:51]
	v_add_f32_e32 v209, v43, v253
	s_mov_b64 exec, -1
	ds_read2_b32 v[246:247], v178 offset0:24 offset1:56
	ds_read2_b32 v[248:249], v178 offset0:25 offset1:57
	ds_read2_b32 v[250:251], v178 offset0:26 offset1:58
	ds_read2_b32 v[252:253], v178 offset0:27 offset1:59
	s_waitcnt lgkmcnt(0)
	s_mov_b64 exec, s[52:53]
	v_add_f32_e32 v194, v60, v246
	s_mov_b64 exec, s[54:55]
	v_add_f32_e32 v210, v44, v247
	s_mov_b64 exec, s[56:57]
	v_add_f32_e32 v195, v61, v248
	s_mov_b64 exec, s[58:59]
	v_add_f32_e32 v211, v45, v249
	s_mov_b64 exec, s[60:61]
	v_add_f32_e32 v196, v62, v250
	s_mov_b64 exec, s[62:63]
	v_add_f32_e32 v212, v46, v251
	s_mov_b64 exec, s[64:65]
	v_add_f32_e32 v197, v63, v252
	s_mov_b64 exec, s[66:67]
	v_add_f32_e32 v213, v47, v253
	s_mov_b64 exec, -1
	s_mov_b64 vcc, -1
.LBB0_488:
	ds_read_b64_tr_b16 v[32:33], v111 offset:0
	ds_read_b64_tr_b16 v[34:35], v111 offset:0x800
	ds_read_b64_tr_b16 v[36:37], v111 offset:0x1000
	ds_read_b64_tr_b16 v[38:39], v111 offset:0x1800
	ds_read_b64_tr_b16 v[40:41], v111 offset:0x2000
	ds_read_b64_tr_b16 v[42:43], v111 offset:0x2800
	ds_read_b64_tr_b16 v[44:45], v111 offset:0x3000
	ds_read_b64_tr_b16 v[46:47], v111 offset:0x3800
	s_waitcnt lgkmcnt(0)
	ds_read_b64_tr_b16 v[48:49], v111 offset:0x200
	ds_read_b64_tr_b16 v[50:51], v111 offset:0xa00
	ds_read_b64_tr_b16 v[52:53], v111 offset:0x1200
	ds_read_b64_tr_b16 v[54:55], v111 offset:0x1a00
	ds_read_b64_tr_b16 v[56:57], v111 offset:0x2200
	ds_read_b64_tr_b16 v[58:59], v111 offset:0x2a00
	ds_read_b64_tr_b16 v[60:61], v111 offset:0x3200
	ds_read_b64_tr_b16 v[62:63], v111 offset:0x3a00
	s_nop 0
	v_mfma_f32_32x32x16_bf16 v[16:31], v[64:67], v[32:35], v[16:31]
	v_exp_f32_e32 v179, v179
	v_exp_f32_e32 v180, v180
	v_exp_f32_e32 v181, v181
	v_exp_f32_e32 v185, v185
	v_exp_f32_e32 v186, v186
	v_exp_f32_e32 v187, v187
	v_exp_f32_e32 v188, v188
	v_mfma_f32_32x32x16_bf16 v[16:31], v[76:79], v[36:39], v[16:31]
	v_exp_f32_e32 v189, v189
	v_exp_f32_e32 v190, v190
	v_exp_f32_e32 v191, v191
	v_exp_f32_e32 v192, v192
	v_exp_f32_e32 v193, v193
	v_exp_f32_e32 v194, v194
	v_exp_f32_e32 v195, v195
	v_mfma_f32_32x32x16_bf16 v[16:31], v[96:99], v[40:43], v[16:31]
	v_exp_f32_e32 v196, v196
	v_exp_f32_e32 v197, v197
	v_mfma_f32_32x32x16_bf16 v[16:31], v[100:103], v[44:47], v[16:31]
	s_waitcnt lgkmcnt(0)
	v_mfma_f32_32x32x16_bf16 v[0:15], v[64:67], v[48:51], v[0:15]
	v_exp_f32_e32 v198, v198
	v_exp_f32_e32 v199, v199
	v_exp_f32_e32 v200, v200
	v_exp_f32_e32 v201, v201
	v_exp_f32_e32 v202, v202
	v_exp_f32_e32 v203, v203
	v_exp_f32_e32 v204, v204
	v_mfma_f32_32x32x16_bf16 v[0:15], v[76:79], v[52:55], v[0:15]
	v_exp_f32_e32 v205, v205
	v_exp_f32_e32 v206, v206
	v_exp_f32_e32 v207, v207
	v_exp_f32_e32 v208, v208
	v_exp_f32_e32 v209, v209
	v_exp_f32_e32 v210, v210
	v_exp_f32_e32 v211, v211
	v_mfma_f32_32x32x16_bf16 v[0:15], v[96:99], v[56:59], v[0:15]
	v_exp_f32_e32 v212, v212
	v_exp_f32_e32 v213, v213
	s_barrier
	s_waitcnt vmcnt(0)
	s_waitcnt vmcnt(1)
	ds_write_b128 v158, v[68:71]
	s_waitcnt vmcnt(0)
	ds_write_b128 v158, v[72:75] offset:8192
	v_mfma_f32_32x32x16_bf16 v[0:15], v[100:103], v[60:63], v[0:15]
	s_waitcnt lgkmcnt(0)
	s_barrier
; #define SBAR() __builtin_amdgcn_sched_barrier(0)
; #define KFRAG(d0, row) (*reinterpret_cast<const bf16x8*>(Ks + KSWZ((row), (half * 64 + (d0) * 16 + hi * 8) * 2)))
; __device__ __forceinline__ void finishSM(f32x16& p0, f32x16& p1, float& l_reg, bf16x8& pa0, bf16x8& pa1, bf16x8& pa2, bf16x8& pa3) {
;     float ps = 0;
; #pragma unroll
;     for (int r = 0; r < 16; ++r) ps += p0[r];
; #pragma unroll
;     for (int r = 0; r < 16; ++r) ps += p1[r];
;     l_reg += ps;
;     ...
;     PK4(p0, 0, pa0); PK4(p0, 8, pa1); PK4(p1, 0, pa2); PK4(p1, 8, pa3);
;     ...
; }
; __device__ __forceinline__ void qkt(f32x16& p0, f32x16& p1, const char* Ks, const bf16x8* qr, float c0, int r32, int hi, int half) {
;     ...
;     bf16x8 a0 = KFRAG(0, r32), a1 = KFRAG(0, 32 + r32), b0 = KFRAG(1, r32), b1 = KFRAG(1, 32 + r32);
;     SBAR();
; #pragma unroll
;     for (int r = 0; r < 16; ++r) { p0[r] = c0; p1[r] = c0; }
;     SBAR();
;     p0 = __builtin_amdgcn_mfma_f32_32x32x16_bf16(a0, qr[0], p0, 0, 0, 0); p1 = __builtin_amdgcn_mfma_f32_32x32x16_bf16(a1, qr[0], p1, 0, 0, 0);
;     a0 = KFRAG(2, r32); a1 = KFRAG(2, 32 + r32);
;     SBAR();
;     p0 = __builtin_amdgcn_mfma_f32_32x32x16_bf16(b0, qr[1], p0, 0, 0, 0); p1 = __builtin_amdgcn_mfma_f32_32x32x16_bf16(b1, qr[1], p1, 0, 0, 0);
;     b0 = KFRAG(3, r32); b1 = KFRAG(3, 32 + r32);
;     SBAR();
;     p0 = __builtin_amdgcn_mfma_f32_32x32x16_bf16(a0, qr[2], p0, 0, 0, 0); p1 = __builtin_amdgcn_mfma_f32_32x32x16_bf16(a1, qr[2], p1, 0, 0, 0);
;     p0 = __builtin_amdgcn_mfma_f32_32x32x16_bf16(b0, qr[3], p0, 0, 0, 0); p1 = __builtin_amdgcn_mfma_f32_32x32x16_bf16(b1, qr[3], p1, 0, 0, 0);
	ds_read_b128 v[32:35], v113 offset:32768
	ds_read_b128 v[96:99], v113 offset:40960
	ds_read_b128 v[100:103], v114 offset:32768
	ds_read_b128 v[214:217], v114 offset:40960
	v_readlane_b32 s72, v255, 10
	v_readlane_b32 s73, v255, 11
	v_readlane_b32 s77, v255, 15
	v_readlane_b32 s79, v255, 17
	v_readlane_b32 s86, v255, 24
	v_readlane_b32 s87, v255, 25
	s_nop 1
	v_mov_b64_e32 v[64:65], s[72:73]
	v_mov_b64_e32 v[66:67], s[72:73]
	v_mov_b64_e32 v[68:69], s[72:73]
	v_mov_b64_e32 v[70:71], s[72:73]
	v_mov_b64_e32 v[72:73], s[72:73]
	v_mov_b64_e32 v[74:75], s[72:73]
	v_mov_b64_e32 v[76:77], s[72:73]
	v_mov_b64_e32 v[78:79], s[72:73]
	s_waitcnt lgkmcnt(3)
	s_nop 0
	v_mfma_f32_32x32x16_bf16 v[48:63], v[32:35], v[92:95], v[64:79]
	s_waitcnt lgkmcnt(2)
	v_mfma_f32_32x32x16_bf16 v[32:47], v[96:99], v[92:95], v[64:79]
	s_nop 6
	ds_read_b128 v[64:67], v115 offset:32768
	ds_read_b128 v[68:71], v115 offset:40960
	s_waitcnt lgkmcnt(3)
	v_mfma_f32_32x32x16_bf16 v[48:63], v[100:103], v[88:91], v[48:63]
	ds_read_b128 v[72:75], v116 offset:32768
	ds_read_b128 v[76:79], v116 offset:40960
	s_waitcnt lgkmcnt(4)
	v_mfma_f32_32x32x16_bf16 v[32:47], v[214:217], v[88:91], v[32:47]
	s_waitcnt lgkmcnt(3)
	v_mfma_f32_32x32x16_bf16 v[48:63], v[64:67], v[84:87], v[48:63]
	v_cvt_pk_bf16_f32 v64, v179, v180
	v_cvt_pk_bf16_f32 v65, v181, v185
	v_cvt_pk_bf16_f32 v66, v186, v187
	v_cvt_pk_bf16_f32 v67, v188, v189
	v_cvt_pk_bf16_f32 v96, v198, v199
	v_cvt_pk_bf16_f32 v97, v200, v201
	v_cvt_pk_bf16_f32 v98, v202, v203
	s_waitcnt lgkmcnt(2)
	v_mfma_f32_32x32x16_bf16 v[32:47], v[68:71], v[84:87], v[32:47]
	v_cvt_pk_bf16_f32 v99, v204, v205
	v_cvt_pk_bf16_f32 v100, v206, v207
	v_cvt_pk_bf16_f32 v101, v208, v209
	v_cvt_pk_bf16_f32 v102, v210, v211
	v_cvt_pk_bf16_f32 v103, v212, v213
	v_permlane32_swap_b32_e32 v64, v66
	s_waitcnt lgkmcnt(1)
	v_mfma_f32_32x32x16_bf16 v[48:63], v[72:75], v[80:83], v[48:63]
	v_permlane32_swap_b32_e32 v65, v67
	v_permlane32_swap_b32_e32 v96, v98
	v_permlane32_swap_b32_e32 v97, v99
	v_permlane32_swap_b32_e32 v100, v102
	s_waitcnt lgkmcnt(0)
	v_mfma_f32_32x32x16_bf16 v[32:47], v[76:79], v[80:83], v[32:47]
	v_cvt_pk_bf16_f32 v76, v190, v191
	v_cvt_pk_bf16_f32 v77, v192, v193
	v_cvt_pk_bf16_f32 v78, v194, v195
	v_cvt_pk_bf16_f32 v79, v196, v197
	s_nop 0
	v_permlane32_swap_b32_e32 v76, v78
	v_permlane32_swap_b32_e32 v77, v79
	v_permlane32_swap_b32_e32 v101, v103
	s_add_i32 s1, s1, 3
	s_min_i32 s1, s1, s71
	s_lshl_b32 s72, s1, 6
	s_mul_i32 s1, s1, 0x50000
	s_mul_hi_i32 s75, s72, 0x1400
	s_add_u32 s72, s33, s1
	s_addc_u32 s73, s92, s75
	s_add_u32 s74, s89, s1
	s_addc_u32 s75, s2, s75
	v_lshl_add_u64 v[68:69], s[74:75], 0, v[144:145]
	s_mov_b32 s74, 0x28000
	v_add_co_u32_e32 v72, vcc, s74, v68
	s_add_i32 s1, s96, 0xffffc000
	s_nop 0
	v_addc_co_u32_e32 v73, vcc, 0, v69, vcc
	global_load_dwordx4 v[68:71], v[68:69], off
	s_nop 0
	global_load_dwordx4 v[72:75], v[72:73], off
	s_and_b32 s1, s1, 0x4000
	v_lshl_add_u64 v[182:183], s[72:73], 0, v[104:105]
	s_mov_b64 s[72:73], 0xe00
	s_add_i32 s1, s1, s70
	v_lshl_add_u64 v[214:215], v[182:183], 0, s[72:73]
	s_mov_b32 s72, m0
	s_mov_b32 m0, s1
	s_nop 0
	global_load_lds_dwordx4 v[214:215], off
	s_mov_b32 m0, s72
	s_mov_b64 s[72:73], 0x28e00
	v_lshl_add_u64 v[182:183], v[182:183], 0, s[72:73]
	s_addk_i32 s1, 0x2000
	s_mov_b32 s72, m0
	s_mov_b32 m0, s1
	s_nop 0
	global_load_lds_dwordx4 v[182:183], off
	s_mov_b32 m0, s72
	s_cmp_ge_i32 s0, s3
	s_cselect_b64 s[72:73], -1, 0
	s_cmp_lt_i32 s0, s91
	s_cselect_b64 s[0:1], -1, 0
	s_and_b64 s[0:1], s[72:73], s[0:1]
	v_mov_b32_e32 v245, 0xf149f2ca
	s_andn2_b64 vcc, exec, s[0:1]
	v_mov_b32_e32 v244, 0xf149f2ca
	v_mov_b32_e32 v242, 0xf149f2ca
	v_mov_b32_e32 v241, 0xf149f2ca
	v_mov_b32_e32 v239, 0xf149f2ca
	v_mov_b32_e32 v236, 0xf149f2ca
	v_mov_b32_e32 v234, 0xf149f2ca
	v_mov_b32_e32 v232, 0xf149f2ca
	v_mov_b32_e32 v231, 0xf149f2ca
	v_mov_b32_e32 v229, 0xf149f2ca
	v_mov_b32_e32 v227, 0xf149f2ca
	v_mov_b32_e32 v225, 0xf149f2ca
	v_mov_b32_e32 v222, 0xf149f2ca
	v_mov_b32_e32 v220, 0xf149f2ca
	v_mov_b32_e32 v218, 0xf149f2ca
	v_mov_b32_e32 v216, 0xf149f2ca
	v_mov_b32_e32 v240, 0xf149f2ca
	v_mov_b32_e32 v238, 0xf149f2ca
	v_mov_b32_e32 v237, 0xf149f2ca
	v_mov_b32_e32 v235, 0xf149f2ca
	v_mov_b32_e32 v233, 0xf149f2ca
	v_mov_b32_e32 v230, 0xf149f2ca
	v_mov_b32_e32 v228, 0xf149f2ca
	v_mov_b32_e32 v226, 0xf149f2ca
	v_mov_b32_e32 v224, 0xf149f2ca
	v_mov_b32_e32 v223, 0xf149f2ca
	v_mov_b32_e32 v221, 0xf149f2ca
	v_mov_b32_e32 v219, 0xf149f2ca
	v_mov_b32_e32 v217, 0xf149f2ca
	v_mov_b32_e32 v215, 0xf149f2ca
	v_mov_b32_e32 v214, 0xf149f2ca
	v_mov_b32_e32 v243, 0xf149f2ca
	s_cbranch_vccnz .LBB0_554
; template <int MODE>
; __device__ __forceinline__ void attn_unit(const UnitArgs& A, char* lds, const int wave_) {
;     ...
;             const int kr = A.tile0 + t, rq = A.q0 + (qb >> 1);
;             int rs = rq - 4; rs = rs < 0 ? 0 : rs; rs = rs > A.R - 8 ? A.R - 8 : rs;
;             if (kr < rs || kr >= rs + 8) {
; #pragma unroll
;                 for (int r = 0; r < 16; ++r) { p0[r] = NEG; p1[r] = NEG; }
;             } else {
;                 const int c = 32 * (qb & 1) + r32; int cs = c - 8; cs = cs < 0 ? 0 : cs; cs = cs > 48 ? 48 : cs;
;                 const float* b = lutB + ((2 * A.h + half) * 15 + (kr - rq + 7)) * 128 + 64 + 4 * hi - c;
; #pragma unroll
;                 for (int r = 0; r < 16; ++r) { const int cc = (r & 3) + 8 * (r >> 2), j = 4 * hi + cc;
;                     p0[r] = ((unsigned)(j - cs) < 16u) ? p0[r] + b[cc] : NEG; p1[r] = ((unsigned)(j + 32 - cs) < 16u) ? p1[r] + b[32 + cc] : NEG; } }
	ds_read2_b32 v[246:247], v178 offset0:128 offset1:160
	ds_read2_b32 v[248:249], v178 offset0:129 offset1:161
	ds_read2_b32 v[250:251], v178 offset0:130 offset1:162
	ds_read2_b32 v[252:253], v178 offset0:131 offset1:163
	s_waitcnt lgkmcnt(0)
	s_mov_b64 exec, s[68:69]
	v_add_f32_e32 v216, v48, v246
	s_mov_b64 exec, s[4:5]
	v_add_f32_e32 v214, v32, v247
	s_mov_b64 exec, s[6:7]
	v_add_f32_e32 v218, v49, v248
	s_mov_b64 exec, s[8:9]
	v_add_f32_e32 v215, v33, v249
	s_mov_b64 exec, s[10:11]
	v_add_f32_e32 v220, v50, v250
	s_mov_b64 exec, s[12:13]
	v_add_f32_e32 v217, v34, v251
	s_mov_b64 exec, s[14:15]
	v_add_f32_e32 v222, v51, v252
	s_mov_b64 exec, s[16:17]
	v_add_f32_e32 v219, v35, v253
	s_mov_b64 exec, -1
	ds_read2_b32 v[246:247], v178 offset0:136 offset1:168
	ds_read2_b32 v[248:249], v178 offset0:137 offset1:169
	ds_read2_b32 v[250:251], v178 offset0:138 offset1:170
	ds_read2_b32 v[252:253], v178 offset0:139 offset1:171
	s_waitcnt lgkmcnt(0)
	s_mov_b64 exec, s[18:19]
	v_add_f32_e32 v225, v52, v246
	s_mov_b64 exec, s[20:21]
	v_add_f32_e32 v221, v36, v247
	s_mov_b64 exec, s[22:23]
	v_add_f32_e32 v227, v53, v248
	s_mov_b64 exec, s[24:25]
	v_add_f32_e32 v223, v37, v249
	s_mov_b64 exec, s[26:27]
	v_add_f32_e32 v229, v54, v250
	s_mov_b64 exec, s[28:29]
	v_add_f32_e32 v224, v38, v251
	s_mov_b64 exec, s[30:31]
	v_add_f32_e32 v231, v55, v252
	s_mov_b64 exec, s[34:35]
	v_add_f32_e32 v226, v39, v253
	s_mov_b64 exec, -1
	ds_read2_b32 v[246:247], v178 offset0:144 offset1:176
	ds_read2_b32 v[248:249], v178 offset0:145 offset1:177
	ds_read2_b32 v[250:251], v178 offset0:146 offset1:178
	ds_read2_b32 v[252:253], v178 offset0:147 offset1:179
	s_waitcnt lgkmcnt(0)
	s_mov_b64 exec, s[36:37]
	v_add_f32_e32 v232, v56, v246
	s_mov_b64 exec, s[38:39]
	v_add_f32_e32 v228, v40, v247
	s_mov_b64 exec, s[40:41]
	v_add_f32_e32 v234, v57, v248
	s_mov_b64 exec, s[42:43]
	v_add_f32_e32 v230, v41, v249
	s_mov_b64 exec, s[44:45]
	v_add_f32_e32 v236, v58, v250
	s_mov_b64 exec, s[46:47]
	v_add_f32_e32 v233, v42, v251
	s_mov_b64 exec, s[48:49]
	v_add_f32_e32 v239, v59, v252
	s_mov_b64 exec, s[50:51]
	v_add_f32_e32 v235, v43, v253
	s_mov_b64 exec, -1
	ds_read2_b32 v[246:247], v178 offset0:152 offset1:184
	ds_read2_b32 v[248:249], v178 offset0:153 offset1:185
	ds_read2_b32 v[250:251], v178 offset0:154 offset1:186
	ds_read2_b32 v[252:253], v178 offset0:155 offset1:187
	s_waitcnt lgkmcnt(0)
	s_mov_b64 exec, s[52:53]
	v_add_f32_e32 v241, v60, v246
	s_mov_b64 exec, s[54:55]
	v_add_f32_e32 v237, v44, v247
	s_mov_b64 exec, s[56:57]
	v_add_f32_e32 v242, v61, v248
	s_mov_b64 exec, s[58:59]
	v_add_f32_e32 v238, v45, v249
	s_mov_b64 exec, s[60:61]
	v_add_f32_e32 v244, v62, v250
	s_mov_b64 exec, s[62:63]
	v_add_f32_e32 v240, v46, v251
	s_mov_b64 exec, s[64:65]
	v_add_f32_e32 v245, v63, v252
	s_mov_b64 exec, s[66:67]
	v_add_f32_e32 v243, v47, v253
	s_mov_b64 exec, -1
	s_mov_b64 vcc, -1
